# one 4-byte pad after the input-projection GEMM so the later GEMM loops keep the baseline 8-byte code placement
# speedup vs baseline: 1.0010x; 1.0010x over previous
; #define GAS __attribute__((address_space(1)))
; #define LAS __attribute__((address_space(3)))
; __device__ __forceinline__ int launder_v(int v) { asm volatile("" : "+v"(v)); return v; }
; __device__ __forceinline__ int grid_x() { int g = (int)gridDim.x; asm volatile("" : "+s"(g)); return g; }
; __device__ __forceinline__ unsigned f2bf(float f) { return (unsigned)__builtin_bit_cast(unsigned short, (__bf16)f); }
; __device__ __forceinline__ void phase_ssd(const Params& P, int seg, unsigned char* smem) {
;     ...
;     const int tid = launder_v(threadIdx.x), lane = tid & 63, w = tid >> 6, fr = lane & 15, fq = lane >> 4;
;     const unsigned lds0 = (unsigned)(size_t)(LAS unsigned char*)smem;
;     bf16* StS = (bf16*)(smem + T_ST); float* acS = (float*)(smem + T_AC);
;     const int lt = w >> 1, pt = w & 1, tq = (lane & 15) >> 2, tp = lane & 3;
;     if (__builtin_amdgcn_readfirstlane(tid) >= 256) __builtin_amdgcn_s_setprio(1);
;     const int gx = grid_x();
;     for (int item = blockIdx.x; item < 256; item += gx) {
;         const int xcd = item & 7, ix = item >> 3, bg = xcd * 2 + (ix >> 4), b = bg >> 3, g = bg & 7, h = g * 8 + ((ix & 15) >> 1), ph = ix & 1;
;         const float Dh = P.d_skip[h];
;         const GAS float* stg = state + (size_t)(seg & 1) * (2 * 64 * 64 * 128) + ((size_t)(b * 64 + h) * 64 + ph * 32) * 128;
;         GAS float* stw = state + (size_t)((seg + 1) & 1) * (2 * 64 * 64 * 128) + ((size_t)(b * 64 + h) * 64 + ph * 32) * 128;
;         f32x4 st[2];
; #pragma unroll
;         for (int p2 = 0; p2 < 2; ++p2)
; #pragma unroll
;             for (int j = 0; j < 4; ++j) st[p2][j] = (seg == 0) ? 0.f : stg[(size_t)(p2 * 16 + fq * 4 + j) * 128 + w * 16 + fr];
;         __syncthreads();
; #pragma unroll
;         for (int p2 = 0; p2 < 2; ++p2)
; #pragma unroll
;             for (int j = 0; j < 4; ++j) StS[(p2 * 16 + fq * 4 + j) * 136 + w * 16 + fr] = (bf16)f2bf(st[p2][j]);
;         const int nchunks = TSEG / 64 + (seg == 0 ? 1 : 0);
.LBB0_292:
	v_readlane_b32 s14, v253, 47
	v_readlane_b32 s15, v253, 48
	s_mov_b32 s9, s82
	s_andn2_b64 vcc, exec, s[14:15]
	v_cndmask_b32_e64 v4, 0, 1, s[14:15]
	v_cmp_ne_u32_e64 s[16:17], 1, v4
	s_nop 1
	v_writelane_b32 v255, s16, 7
	s_nop 1
	v_writelane_b32 v255, s17, 8
	s_cbranch_vccnz .LBB0_338
	s_nop 0
	s_mov_b64 exec, -1
	s_mov_b64 s[0:1], s[80:81]
	s_mov_b32 s63, s82
	v_readlane_b32 s24, v254, 38
	v_readlane_b32 s52, v252, 28
	v_readlane_b32 s53, v252, 29
	v_and_b32_e32 v184, 63, v172
	v_lshrrev_b32_e32 v185, 6, v172
	v_and_b32_e32 v186, 15, v172
	v_bfe_u32 v187, v172, 4, 2
	v_bfe_u32 v188, v172, 2, 2
	v_and_b32_e32 v189, 3, v172
	v_lshrrev_b32_e32 v190, 7, v172
	v_lshrrev_b32_e32 v191, 8, v172
	v_xor_b32_e32 v190, v190, v191
	v_bfe_u32 v191, v172, 6, 1
	v_readfirstlane_b32 s73, v185
	s_nop 3
	s_lshr_b32 s55, s73, 1
	s_lshr_b32 s65, s73, 2
	s_xor_b32 s55, s55, s65
	v_lshrrev_b32_e32 v170, 4, v172
	v_and_b32_e32 v171, 7, v170
	v_lshlrev_b32_e32 v171, 1, v171
	v_xor_b32_e32 v171, v171, v186
	v_lshlrev_b32_e32 v171, 4, v171
	v_lshl_add_u32 v212, v170, 8, v171
	v_lshrrev_b32_e32 v171, 3, v172
	v_and_b32_e32 v192, 7, v172
	v_mul_u32_u24_e32 v214, 80, v171
	v_lshl_add_u32 v214, v192, 3, v214
	v_mul_u32_u24_e32 v216, 72, v171
	v_lshl_add_u32 v216, v192, 3, v216
	v_lshlrev_b32_e32 v218, 2, v171
	v_add_u32_e32 v218, 0x1d800, v218
	v_and_b32_e32 v193, 7, v186
	v_lshlrev_b32_e32 v193, 1, v193
	v_lshl_add_u32 v195, v191, 4, v186
	v_lshlrev_b32_e32 v195, 8, v195
	v_add_u32_e32 v195, 0x19800, v195
	v_add_u32_e32 v170, 0, v187
	v_xor_b32_e32 v170, v170, v193
	v_lshlrev_b32_e32 v170, 4, v170
	v_lshl_add_u32 v219, v186, 8, v170
	v_add_u32_e32 v227, v195, v170
	v_add_u32_e32 v170, 4, v187
	v_xor_b32_e32 v170, v170, v193
	v_lshlrev_b32_e32 v170, 4, v170
	v_lshl_add_u32 v220, v186, 8, v170
	v_add_u32_e32 v228, v195, v170
	v_add_u32_e32 v170, 8, v187
	v_xor_b32_e32 v170, v170, v193
	v_lshlrev_b32_e32 v170, 4, v170
	v_lshl_add_u32 v221, v186, 8, v170
	v_add_u32_e32 v229, v195, v170
	v_add_u32_e32 v170, 12, v187
	v_xor_b32_e32 v170, v170, v193
	v_lshlrev_b32_e32 v170, 4, v170
	v_lshl_add_u32 v222, v186, 8, v170
	v_add_u32_e32 v230, v195, v170
	v_lshlrev_b32_e32 v231, 2, v186
	v_add_u32_e32 v231, 0x1d800, v231
	v_lshlrev_b32_e32 v232, 4, v187
	v_add_u32_e32 v232, 0x1d800, v232
	v_lshl_add_u32 v170, v187, 2, v188
	v_mul_u32_u24_e32 v233, 80, v170
	v_lshl_add_u32 v233, v191, 5, v233
	v_lshl_add_u32 v233, v189, 3, v233
	v_mul_u32_u24_e32 v235, 72, v186
	v_lshl_add_u32 v235, v191, 5, v235
	v_lshl_add_u32 v235, v187, 3, v235
	v_mul_u32_u24_e32 v237, 80, v170
	v_lshl_add_u32 v237, v189, 3, v237
	v_and_b32_e32 v171, 7, v170
	v_lshlrev_b32_e32 v171, 1, v171
	v_lshrrev_b32_e32 v192, 1, v189
	v_and_b32_e32 v195, 1, v189
	v_lshlrev_b32_e32 v195, 3, v195
	v_lshl_add_u32 v195, v170, 8, v195
	v_and_b32_e32 v194, 3, v185
	v_lshl_add_u32 v193, v194, 2, v192
	v_xor_b32_e32 v193, v193, v171
	v_lshl_add_u32 v244, v193, 4, v195
	v_lshl_add_u32 v193, v194, 2, v192
	v_add_u32_e32 v193, 2, v193
	v_xor_b32_e32 v193, v193, v171
	v_lshl_add_u32 v245, v193, 4, v195
	v_and_b32_e32 v171, 7, v186
	v_lshlrev_b32_e32 v171, 1, v171
	v_lshrrev_b32_e32 v192, 1, v187
	v_and_b32_e32 v195, 1, v187
	v_lshlrev_b32_e32 v195, 3, v195
	v_lshl_add_u32 v195, v186, 8, v195
	v_add_u32_e32 v195, 0x19800, v195
	v_lshl_add_u32 v193, v194, 2, v192
	v_xor_b32_e32 v193, v193, v171
	v_lshl_add_u32 v248, v193, 4, v195
	v_lshl_add_u32 v193, v194, 2, v192
	v_add_u32_e32 v193, 2, v193
	v_xor_b32_e32 v193, v193, v171
	v_lshl_add_u32 v249, v193, 4, v195
	v_add_u32_e32 v213, 0xcc00, v212
	v_add_u32_e32 v215, 0xcc00, v214
	v_add_u32_e32 v217, 0xcc00, v216
	v_add_u32_e32 v234, 0xcc00, v233
	v_add_u32_e32 v236, 0xcc00, v235
	v_add_u32_e32 v243, 0xcc00, v237
	v_add_u32_e32 v223, 0xcc00, v219
	v_add_u32_e32 v224, 0xcc00, v220
	v_add_u32_e32 v225, 0xcc00, v221
	v_add_u32_e32 v226, 0xcc00, v222
	v_add_u32_e32 v246, 0xcc00, v244
	v_add_u32_e32 v247, 0xcc00, v245
	v_lshlrev_b32_e32 v170, 2, v187
	v_add_u32_e32 v171, 0, v170
	v_cmp_le_u32_e64 s[14:15], v171, v186
	v_add_u32_e32 v171, 1, v170
	v_cmp_le_u32_e64 s[16:17], v171, v186
	v_add_u32_e32 v171, 2, v170
	v_cmp_le_u32_e64 s[22:23], v171, v186
	v_add_u32_e32 v171, 3, v170
	v_cmp_le_u32_e64 s[34:35], v171, v186
	v_lshlrev_b32_e32 v211, 9, v186
	v_lshl_add_u32 v211, v194, 7, v211
	v_lshl_add_u32 v211, v187, 4, v211
	s_cmp_eq_u32 s24, 0
	s_cselect_b32 s60, 1, 0
	s_add_u32 s39, s60, 64
	s_mov_b32 s18, s2
